# filter MLP hidden layers: k loops fully unrolled with all weight loads in flight (same fmac order)
# speedup vs baseline: 1.0386x; 1.0049x over previous
; DEV void phase_filter_mlp(const Params& p, char* smem) {
;     ...
;       const int pp = tid >> 6, u = tid & 63;
;       {
;         float s = b1[u];
;         for (int k = 0; k < 33; ++k) s += z[pp * 36 + k] * w1[k * 64 + u];
;         h1[pp * 64 + u] = sinf(fr[u] * s);
.LBB0_60:
	v_lshl_add_u64 v[32:33], v[20:21], 0, s[0:1]
	global_load_dword v31, v[32:33], off
	global_load_dword v42, v[32:33], off offset:256
	global_load_dword v43, v[32:33], off offset:512
	global_load_dword v44, v[32:33], off offset:768
	global_load_dword v45, v[32:33], off offset:1024
	global_load_dword v62, v[32:33], off offset:1280
	global_load_dword v63, v[32:33], off offset:1536
	global_load_dword v64, v[32:33], off offset:1792
	global_load_dword v65, v[32:33], off offset:2048
	global_load_dword v66, v[32:33], off offset:2304
	global_load_dword v67, v[32:33], off offset:2560
	s_add_u32 s0, s0, 0xb00
	s_addc_u32 s1, s1, 0
	v_lshl_add_u64 v[32:33], v[20:21], 0, s[0:1]
	global_load_dword v100, v[32:33], off
	global_load_dword v101, v[32:33], off offset:256
	global_load_dword v102, v[32:33], off offset:512
	global_load_dword v103, v[32:33], off offset:768
	global_load_dword v104, v[32:33], off offset:1024
	global_load_dword v105, v[32:33], off offset:1280
	global_load_dword v106, v[32:33], off offset:1536
	global_load_dword v107, v[32:33], off offset:1792
	global_load_dword v108, v[32:33], off offset:2048
	global_load_dword v109, v[32:33], off offset:2304
	global_load_dword v110, v[32:33], off offset:2560
	s_add_u32 s0, s0, 0xb00
	s_addc_u32 s1, s1, 0
	v_lshl_add_u64 v[32:33], v[20:21], 0, s[0:1]
	global_load_dword v116, v[32:33], off
	global_load_dword v117, v[32:33], off offset:256
	global_load_dword v118, v[32:33], off offset:512
	global_load_dword v119, v[32:33], off offset:768
	global_load_dword v120, v[32:33], off offset:1024
	global_load_dword v121, v[32:33], off offset:1280
	global_load_dword v122, v[32:33], off offset:1536
	global_load_dword v123, v[32:33], off offset:1792
	global_load_dword v124, v[32:33], off offset:2048
	global_load_dword v125, v[32:33], off offset:2304
	global_load_dword v126, v[32:33], off offset:2560
	s_add_u32 s0, s0, 0xb00
	s_addc_u32 s1, s1, 0
	ds_read2_b32 v[32:33], v30 offset1:1
	ds_read2_b32 v[34:35], v30 offset0:2 offset1:3
	ds_read2_b32 v[36:37], v30 offset0:4 offset1:5
	ds_read2_b32 v[38:39], v30 offset0:6 offset1:7
	ds_read2_b32 v[40:41], v30 offset0:8 offset1:9
	ds_read_b32 v68, v30 offset:40
	v_add_u32_e32 v30, 44, v30
	s_waitcnt vmcnt(32) lgkmcnt(5)
	v_fmac_f32_e32 v4, v32, v31
	s_waitcnt vmcnt(31)
	v_fmac_f32_e32 v4, v33, v42
	s_waitcnt vmcnt(30) lgkmcnt(4)
	v_fmac_f32_e32 v4, v34, v43
	s_waitcnt vmcnt(29)
	v_fmac_f32_e32 v4, v35, v44
	s_waitcnt vmcnt(28) lgkmcnt(3)
	v_fmac_f32_e32 v4, v36, v45
	s_waitcnt vmcnt(27)
	v_fmac_f32_e32 v4, v37, v62
	s_waitcnt vmcnt(26) lgkmcnt(2)
	v_fmac_f32_e32 v4, v38, v63
	s_waitcnt vmcnt(25)
	v_fmac_f32_e32 v4, v39, v64
	s_waitcnt vmcnt(24) lgkmcnt(1)
	v_fmac_f32_e32 v4, v40, v65
	s_waitcnt vmcnt(23)
	v_fmac_f32_e32 v4, v41, v66
	s_waitcnt vmcnt(22) lgkmcnt(0)
	v_fmac_f32_e32 v4, v68, v67
	ds_read2_b32 v[32:33], v30 offset1:1
	ds_read2_b32 v[34:35], v30 offset0:2 offset1:3
	ds_read2_b32 v[36:37], v30 offset0:4 offset1:5
	ds_read2_b32 v[38:39], v30 offset0:6 offset1:7
	ds_read2_b32 v[40:41], v30 offset0:8 offset1:9
	ds_read_b32 v68, v30 offset:40
	v_add_u32_e32 v30, 44, v30
	s_waitcnt vmcnt(21) lgkmcnt(5)
	v_fmac_f32_e32 v4, v32, v100
	s_waitcnt vmcnt(20)
	v_fmac_f32_e32 v4, v33, v101
	s_waitcnt vmcnt(19) lgkmcnt(4)
	v_fmac_f32_e32 v4, v34, v102
	s_waitcnt vmcnt(18)
	v_fmac_f32_e32 v4, v35, v103
	s_waitcnt vmcnt(17) lgkmcnt(3)
	v_fmac_f32_e32 v4, v36, v104
	s_waitcnt vmcnt(16)
	v_fmac_f32_e32 v4, v37, v105
	s_waitcnt vmcnt(15) lgkmcnt(2)
	v_fmac_f32_e32 v4, v38, v106
	s_waitcnt vmcnt(14)
	v_fmac_f32_e32 v4, v39, v107
	s_waitcnt vmcnt(13) lgkmcnt(1)
	v_fmac_f32_e32 v4, v40, v108
	s_waitcnt vmcnt(12)
	v_fmac_f32_e32 v4, v41, v109
	s_waitcnt vmcnt(11) lgkmcnt(0)
	v_fmac_f32_e32 v4, v68, v110
	ds_read2_b32 v[32:33], v30 offset1:1
	ds_read2_b32 v[34:35], v30 offset0:2 offset1:3
	ds_read2_b32 v[36:37], v30 offset0:4 offset1:5
	ds_read2_b32 v[38:39], v30 offset0:6 offset1:7
	ds_read2_b32 v[40:41], v30 offset0:8 offset1:9
	ds_read_b32 v68, v30 offset:40
	v_add_u32_e32 v30, 44, v30
	s_waitcnt vmcnt(10) lgkmcnt(5)
	v_fmac_f32_e32 v4, v32, v116
	s_waitcnt vmcnt(9)
	v_fmac_f32_e32 v4, v33, v117
	s_waitcnt vmcnt(8) lgkmcnt(4)
	v_fmac_f32_e32 v4, v34, v118
	s_waitcnt vmcnt(7)
	v_fmac_f32_e32 v4, v35, v119
	s_waitcnt vmcnt(6) lgkmcnt(3)
	v_fmac_f32_e32 v4, v36, v120
	s_waitcnt vmcnt(5)
	v_fmac_f32_e32 v4, v37, v121
	s_waitcnt vmcnt(4) lgkmcnt(2)
	v_fmac_f32_e32 v4, v38, v122
	s_waitcnt vmcnt(3)
	v_fmac_f32_e32 v4, v39, v123
	s_waitcnt vmcnt(2) lgkmcnt(1)
	v_fmac_f32_e32 v4, v40, v124
	s_waitcnt vmcnt(1)
	v_fmac_f32_e32 v4, v41, v125
	s_waitcnt vmcnt(0) lgkmcnt(0)
	v_fmac_f32_e32 v4, v68, v126
	global_load_dword v30, v[8:9], off
	s_waitcnt vmcnt(0)
	v_mul_f32_e32 v30, v4, v30
	v_and_b32_e32 v31, 0x7fffffff, v30
	v_cmp_nlt_f32_e64 s[0:1], |v30|, s36
	s_and_saveexec_b64 s[4:5], s[0:1]
	s_xor_b64 s[20:21], exec, s[4:5]
	s_cbranch_execz .LBB0_63
; DEV void phase_filter_mlp(const Params& p, char* smem) {
;     ...
;         h1[pp * 64 + u] = sinf(fr[u] * s);
	v_lshrrev_b32_e32 v4, 23, v31
	v_add_u32_e32 v4, 0xffffff88, v4
	v_cmp_lt_u32_e32 vcc, 63, v4
	s_nop 1
	v_cndmask_b32_e32 v32, 0, v55, vcc
	v_add_u32_e32 v4, v32, v4
	v_cmp_lt_u32_e64 s[0:1], 31, v4
	s_nop 1
	v_cndmask_b32_e64 v32, 0, v56, s[0:1]
	v_add_u32_e32 v4, v32, v4
	v_cmp_lt_u32_e64 s[4:5], 31, v4
	s_nop 1
	v_cndmask_b32_e64 v32, 0, v56, s[4:5]
	v_add_u32_e32 v62, v32, v4
	v_and_b32_e32 v4, 0x7fffff, v31
	v_or_b32_e32 v44, 0x800000, v4
	v_mad_u64_u32 v[32:33], s[8:9], v44, s37, 0
	v_mov_b32_e32 v4, v33
	v_mad_u64_u32 v[34:35], s[8:9], v44, s38, v[4:5]
	v_mov_b32_e32 v4, v35
	v_mad_u64_u32 v[36:37], s[8:9], v44, s39, v[4:5]
	v_mov_b32_e32 v4, v37
	v_mad_u64_u32 v[38:39], s[8:9], v44, s40, v[4:5]
	v_mov_b32_e32 v4, v39
	v_mad_u64_u32 v[40:41], s[8:9], v44, s41, v[4:5]
	v_mov_b32_e32 v4, v41
	v_mad_u64_u32 v[42:43], s[8:9], v44, s42, v[4:5]
	v_mov_b32_e32 v4, v43
	v_mad_u64_u32 v[44:45], s[8:9], v44, s43, v[4:5]
	v_cndmask_b32_e32 v33, v42, v38, vcc
	v_cndmask_b32_e32 v4, v44, v40, vcc
	v_cndmask_b32_e32 v37, v45, v42, vcc
	v_cndmask_b32_e64 v35, v4, v33, s[0:1]
	v_cndmask_b32_e64 v4, v37, v4, s[0:1]
	v_cndmask_b32_e32 v37, v40, v36, vcc
	v_cndmask_b32_e64 v33, v33, v37, s[0:1]
	v_cndmask_b32_e32 v34, v38, v34, vcc
	v_cndmask_b32_e64 v4, v4, v35, s[4:5]
	v_cndmask_b32_e64 v35, v35, v33, s[4:5]
	v_sub_u32_e32 v39, 32, v62
	v_cndmask_b32_e64 v37, v37, v34, s[0:1]
	v_alignbit_b32 v40, v4, v35, v39
	v_cmp_eq_u32_e64 s[8:9], 0, v62
	v_cndmask_b32_e64 v33, v33, v37, s[4:5]
	v_cndmask_b32_e32 v32, v36, v32, vcc
	v_cndmask_b32_e64 v4, v40, v4, s[8:9]
	v_alignbit_b32 v38, v35, v33, v39
	v_cndmask_b32_e64 v32, v34, v32, s[0:1]
	v_cndmask_b32_e64 v35, v38, v35, s[8:9]
	v_bfe_u32 v41, v4, 29, 1
	v_cndmask_b32_e64 v32, v37, v32, s[4:5]
	v_alignbit_b32 v38, v4, v35, 30
	v_sub_u32_e32 v42, 0, v41
	v_alignbit_b32 v34, v33, v32, v39
	v_xor_b32_e32 v38, v38, v42
	v_cndmask_b32_e64 v33, v34, v33, s[8:9]
	v_alignbit_b32 v34, v35, v33, 30
	v_ffbh_u32_e32 v35, v38
	v_min_u32_e32 v35, 32, v35
	v_alignbit_b32 v32, v33, v32, 30
	v_xor_b32_e32 v34, v34, v42
	v_sub_u32_e32 v36, 31, v35
	v_xor_b32_e32 v32, v32, v42
	v_alignbit_b32 v37, v38, v34, v36
	v_alignbit_b32 v32, v34, v32, v36
	v_alignbit_b32 v33, v37, v32, 9
	v_ffbh_u32_e32 v34, v33
	v_min_u32_e32 v34, 32, v34
	v_lshrrev_b32_e32 v40, 29, v4
	v_not_b32_e32 v36, v34
	v_alignbit_b32 v32, v33, v32, v36
	v_lshlrev_b32_e32 v33, 31, v40
	v_or_b32_e32 v36, 0x33000000, v33
	v_add_lshl_u32 v34, v34, v35, 23
	v_lshrrev_b32_e32 v32, 9, v32
	v_sub_u32_e32 v34, v36, v34
	v_or_b32_e32 v33, 0.5, v33
	v_lshlrev_b32_e32 v35, 23, v35
	v_or_b32_e32 v32, v34, v32
	v_lshrrev_b32_e32 v34, 9, v37
	v_sub_u32_e32 v33, v33, v35
	v_or_b32_e32 v33, v34, v33
	v_mul_f32_e32 v34, 0x3fc90fda, v33
	v_fma_f32 v35, v33, s44, -v34
	v_fmac_f32_e32 v35, 0x33a22168, v33
	v_fmac_f32_e32 v35, 0x3fc90fda, v32
	v_lshrrev_b32_e32 v4, 30, v4
	v_add_f32_e32 v32, v34, v35
	v_add_u32_e32 v4, v41, v4

; DEV void phase_filter_mlp(const Params& p, char* smem) {
;     ...
;       {
;         float s = b2[u];
;         for (int k = 0; k < 64; ++k) s += h1[pp * 64 + k] * w2[k * 64 + u];
;         h2[pp * 64 + u] = sinf(fr[64 + u] * s);
.LBB0_66:
	v_lshl_add_u64 v[32:33], v[22:23], 0, s[0:1]
	global_load_dword v31, v[32:33], off
	global_load_dword v44, v[32:33], off offset:256
	global_load_dword v45, v[32:33], off offset:512
	global_load_dword v66, v[32:33], off offset:768
	global_load_dword v67, v[32:33], off offset:1024
	global_load_dword v68, v[32:33], off offset:1280
	global_load_dword v69, v[32:33], off offset:1536
	global_load_dword v70, v[32:33], off offset:1792
	global_load_dword v71, v[32:33], off offset:2048
	global_load_dword v72, v[32:33], off offset:2304
	global_load_dword v73, v[32:33], off offset:2560
	global_load_dword v74, v[32:33], off offset:2816
	global_load_dword v75, v[32:33], off offset:3072
	global_load_dword v76, v[32:33], off offset:3328
	global_load_dword v77, v[32:33], off offset:3584
	global_load_dword v78, v[32:33], off offset:3840
	s_add_u32 s0, s0, 0x1000
	s_addc_u32 s1, s1, 0
	v_lshl_add_u64 v[32:33], v[22:23], 0, s[0:1]
	global_load_dword v100, v[32:33], off
	global_load_dword v101, v[32:33], off offset:256
	global_load_dword v102, v[32:33], off offset:512
	global_load_dword v103, v[32:33], off offset:768
	global_load_dword v104, v[32:33], off offset:1024
	global_load_dword v105, v[32:33], off offset:1280
	global_load_dword v106, v[32:33], off offset:1536
	global_load_dword v107, v[32:33], off offset:1792
	global_load_dword v108, v[32:33], off offset:2048
	global_load_dword v109, v[32:33], off offset:2304
	global_load_dword v110, v[32:33], off offset:2560
	global_load_dword v111, v[32:33], off offset:2816
	global_load_dword v112, v[32:33], off offset:3072
	global_load_dword v113, v[32:33], off offset:3328
	global_load_dword v114, v[32:33], off offset:3584
	global_load_dword v115, v[32:33], off offset:3840
	s_add_u32 s0, s0, 0x1000
	s_addc_u32 s1, s1, 0
	v_lshl_add_u64 v[32:33], v[22:23], 0, s[0:1]
	global_load_dword v116, v[32:33], off
	global_load_dword v117, v[32:33], off offset:256
	global_load_dword v118, v[32:33], off offset:512
	global_load_dword v119, v[32:33], off offset:768
	global_load_dword v120, v[32:33], off offset:1024
	global_load_dword v121, v[32:33], off offset:1280
	global_load_dword v122, v[32:33], off offset:1536
	global_load_dword v123, v[32:33], off offset:1792
	global_load_dword v124, v[32:33], off offset:2048
	global_load_dword v125, v[32:33], off offset:2304
	global_load_dword v126, v[32:33], off offset:2560
	global_load_dword v127, v[32:33], off offset:2816
	global_load_dword v128, v[32:33], off offset:3072
	global_load_dword v129, v[32:33], off offset:3328
	global_load_dword v130, v[32:33], off offset:3584
	global_load_dword v131, v[32:33], off offset:3840
	s_add_u32 s0, s0, 0x1000
	s_addc_u32 s1, s1, 0
	v_lshl_add_u64 v[32:33], v[22:23], 0, s[0:1]
	global_load_dword v132, v[32:33], off
	global_load_dword v133, v[32:33], off offset:256
	global_load_dword v134, v[32:33], off offset:512
	global_load_dword v135, v[32:33], off offset:768
	global_load_dword v136, v[32:33], off offset:1024
	global_load_dword v137, v[32:33], off offset:1280
	global_load_dword v138, v[32:33], off offset:1536
	global_load_dword v139, v[32:33], off offset:1792
	global_load_dword v140, v[32:33], off offset:2048
	global_load_dword v141, v[32:33], off offset:2304
	global_load_dword v142, v[32:33], off offset:2560
	global_load_dword v143, v[32:33], off offset:2816
	global_load_dword v144, v[32:33], off offset:3072
	global_load_dword v145, v[32:33], off offset:3328
	global_load_dword v146, v[32:33], off offset:3584
	global_load_dword v147, v[32:33], off offset:3840
	s_add_u32 s0, s0, 0x1000
	s_addc_u32 s1, s1, 0
	ds_read_b128 v[32:35], v30
	ds_read_b128 v[36:39], v30 offset:16
	ds_read_b128 v[40:43], v30 offset:32
	ds_read_b128 v[62:65], v30 offset:48
	v_add_u32_e32 v30, 64, v30
	s_waitcnt vmcnt(63) lgkmcnt(3)
	v_fmac_f32_e32 v4, v32, v31
	s_waitcnt vmcnt(62)
	v_fmac_f32_e32 v4, v33, v44
	s_waitcnt vmcnt(61)
	v_fmac_f32_e32 v4, v34, v45
	s_waitcnt vmcnt(60)
	v_fmac_f32_e32 v4, v35, v66
	s_waitcnt vmcnt(59) lgkmcnt(2)
	v_fmac_f32_e32 v4, v36, v67
	s_waitcnt vmcnt(58)
	v_fmac_f32_e32 v4, v37, v68
	s_waitcnt vmcnt(57)
	v_fmac_f32_e32 v4, v38, v69
	s_waitcnt vmcnt(56)
	v_fmac_f32_e32 v4, v39, v70
	s_waitcnt vmcnt(55) lgkmcnt(1)
	v_fmac_f32_e32 v4, v40, v71
	s_waitcnt vmcnt(54)
	v_fmac_f32_e32 v4, v41, v72
	s_waitcnt vmcnt(53)
	v_fmac_f32_e32 v4, v42, v73
	s_waitcnt vmcnt(52)
	v_fmac_f32_e32 v4, v43, v74
	s_waitcnt vmcnt(51) lgkmcnt(0)
	v_fmac_f32_e32 v4, v62, v75
	s_waitcnt vmcnt(50)
	v_fmac_f32_e32 v4, v63, v76
	s_waitcnt vmcnt(49)
	v_fmac_f32_e32 v4, v64, v77
	s_waitcnt vmcnt(48)
	v_fmac_f32_e32 v4, v65, v78
	ds_read_b128 v[32:35], v30
	ds_read_b128 v[36:39], v30 offset:16
	ds_read_b128 v[40:43], v30 offset:32
	ds_read_b128 v[62:65], v30 offset:48
	v_add_u32_e32 v30, 64, v30
	s_waitcnt vmcnt(47) lgkmcnt(3)
	v_fmac_f32_e32 v4, v32, v100
	s_waitcnt vmcnt(46)
	v_fmac_f32_e32 v4, v33, v101
	s_waitcnt vmcnt(45)
	v_fmac_f32_e32 v4, v34, v102
	s_waitcnt vmcnt(44)
	v_fmac_f32_e32 v4, v35, v103
	s_waitcnt vmcnt(43) lgkmcnt(2)
	v_fmac_f32_e32 v4, v36, v104
	s_waitcnt vmcnt(42)
	v_fmac_f32_e32 v4, v37, v105
	s_waitcnt vmcnt(41)
	v_fmac_f32_e32 v4, v38, v106
	s_waitcnt vmcnt(40)
	v_fmac_f32_e32 v4, v39, v107
	s_waitcnt vmcnt(39) lgkmcnt(1)
	v_fmac_f32_e32 v4, v40, v108
	s_waitcnt vmcnt(38)
	v_fmac_f32_e32 v4, v41, v109
	s_waitcnt vmcnt(37)
	v_fmac_f32_e32 v4, v42, v110
	s_waitcnt vmcnt(36)
	v_fmac_f32_e32 v4, v43, v111
	s_waitcnt vmcnt(35) lgkmcnt(0)
; DEV void phase_filter_mlp(const Params& p, char* smem) {
;     ...
;         for (int k = 0; k < 64; ++k) s += h1[pp * 64 + k] * w2[k * 64 + u];
;         h2[pp * 64 + u] = sinf(fr[64 + u] * s);
	v_fmac_f32_e32 v4, v62, v112
	s_waitcnt vmcnt(34)
	v_fmac_f32_e32 v4, v63, v113
	s_waitcnt vmcnt(33)
	v_fmac_f32_e32 v4, v64, v114
	s_waitcnt vmcnt(32)
	v_fmac_f32_e32 v4, v65, v115
	ds_read_b128 v[32:35], v30
	ds_read_b128 v[36:39], v30 offset:16
	ds_read_b128 v[40:43], v30 offset:32
	ds_read_b128 v[62:65], v30 offset:48
	v_add_u32_e32 v30, 64, v30
	s_waitcnt vmcnt(31) lgkmcnt(3)
	v_fmac_f32_e32 v4, v32, v116
	s_waitcnt vmcnt(30)
	v_fmac_f32_e32 v4, v33, v117
	s_waitcnt vmcnt(29)
	v_fmac_f32_e32 v4, v34, v118
	s_waitcnt vmcnt(28)
	v_fmac_f32_e32 v4, v35, v119
	s_waitcnt vmcnt(27) lgkmcnt(2)
	v_fmac_f32_e32 v4, v36, v120
	s_waitcnt vmcnt(26)
	v_fmac_f32_e32 v4, v37, v121
	s_waitcnt vmcnt(25)
	v_fmac_f32_e32 v4, v38, v122
	s_waitcnt vmcnt(24)
	v_fmac_f32_e32 v4, v39, v123
	s_waitcnt vmcnt(23) lgkmcnt(1)
	v_fmac_f32_e32 v4, v40, v124
	s_waitcnt vmcnt(22)
	v_fmac_f32_e32 v4, v41, v125
	s_waitcnt vmcnt(21)
	v_fmac_f32_e32 v4, v42, v126
	s_waitcnt vmcnt(20)
	v_fmac_f32_e32 v4, v43, v127
	s_waitcnt vmcnt(19) lgkmcnt(0)
	v_fmac_f32_e32 v4, v62, v128
	s_waitcnt vmcnt(18)
	v_fmac_f32_e32 v4, v63, v129
	s_waitcnt vmcnt(17)
	v_fmac_f32_e32 v4, v64, v130
	s_waitcnt vmcnt(16)
	v_fmac_f32_e32 v4, v65, v131
	ds_read_b128 v[32:35], v30
	ds_read_b128 v[36:39], v30 offset:16
	ds_read_b128 v[40:43], v30 offset:32
	ds_read_b128 v[62:65], v30 offset:48
	v_add_u32_e32 v30, 64, v30
	s_waitcnt vmcnt(15) lgkmcnt(3)
	v_fmac_f32_e32 v4, v32, v132
	s_waitcnt vmcnt(14)
	v_fmac_f32_e32 v4, v33, v133
	s_waitcnt vmcnt(13)
	v_fmac_f32_e32 v4, v34, v134
	s_waitcnt vmcnt(12)
	v_fmac_f32_e32 v4, v35, v135
	s_waitcnt vmcnt(11) lgkmcnt(2)
	v_fmac_f32_e32 v4, v36, v136
	s_waitcnt vmcnt(10)
	v_fmac_f32_e32 v4, v37, v137
	s_waitcnt vmcnt(9)
	v_fmac_f32_e32 v4, v38, v138
	s_waitcnt vmcnt(8)
	v_fmac_f32_e32 v4, v39, v139
	s_waitcnt vmcnt(7) lgkmcnt(1)
	v_fmac_f32_e32 v4, v40, v140
	s_waitcnt vmcnt(6)
	v_fmac_f32_e32 v4, v41, v141
	s_waitcnt vmcnt(5)
	v_fmac_f32_e32 v4, v42, v142
	s_waitcnt vmcnt(4)
	v_fmac_f32_e32 v4, v43, v143
	s_waitcnt vmcnt(3) lgkmcnt(0)
	v_fmac_f32_e32 v4, v62, v144
	s_waitcnt vmcnt(2)
	v_fmac_f32_e32 v4, v63, v145
	s_waitcnt vmcnt(1)
	v_fmac_f32_e32 v4, v64, v146
	s_waitcnt vmcnt(0)
	v_fmac_f32_e32 v4, v65, v147
	global_load_dword v30, v[8:9], off offset:256
	s_waitcnt vmcnt(0)
	v_mul_f32_e32 v30, v4, v30
	v_and_b32_e32 v31, 0x7fffffff, v30
	v_cmp_nlt_f32_e64 s[0:1], |v30|, s36
	s_and_saveexec_b64 s[4:5], s[0:1]
	s_xor_b64 s[20:21], exec, s[4:5]
	s_cbranch_execz .LBB0_69
	v_lshrrev_b32_e32 v4, 23, v31
	v_add_u32_e32 v4, 0xffffff88, v4
	v_cmp_lt_u32_e32 vcc, 63, v4
	s_nop 1
	v_cndmask_b32_e32 v32, 0, v55, vcc
	v_add_u32_e32 v4, v32, v4
	v_cmp_lt_u32_e64 s[0:1], 31, v4
	s_nop 1
	v_cndmask_b32_e64 v32, 0, v56, s[0:1]
	v_add_u32_e32 v4, v32, v4
	v_cmp_lt_u32_e64 s[4:5], 31, v4
	s_nop 1
	v_cndmask_b32_e64 v32, 0, v56, s[4:5]
	v_add_u32_e32 v62, v32, v4
	v_and_b32_e32 v4, 0x7fffff, v31
	v_or_b32_e32 v44, 0x800000, v4
	v_mad_u64_u32 v[32:33], s[8:9], v44, s37, 0
	v_mov_b32_e32 v4, v33
	v_mad_u64_u32 v[34:35], s[8:9], v44, s38, v[4:5]
	v_mov_b32_e32 v4, v35
	v_mad_u64_u32 v[36:37], s[8:9], v44, s39, v[4:5]
	v_mov_b32_e32 v4, v37
	v_mad_u64_u32 v[38:39], s[8:9], v44, s40, v[4:5]
	v_mov_b32_e32 v4, v39
	v_mad_u64_u32 v[40:41], s[8:9], v44, s41, v[4:5]
	v_mov_b32_e32 v4, v41
	v_mad_u64_u32 v[42:43], s[8:9], v44, s42, v[4:5]
	v_mov_b32_e32 v4, v43
	v_mad_u64_u32 v[44:45], s[8:9], v44, s43, v[4:5]
	v_cndmask_b32_e32 v33, v42, v38, vcc
	v_cndmask_b32_e32 v4, v44, v40, vcc
	v_cndmask_b32_e32 v37, v45, v42, vcc
	v_cndmask_b32_e64 v35, v4, v33, s[0:1]
	v_cndmask_b32_e64 v4, v37, v4, s[0:1]
	v_cndmask_b32_e32 v37, v40, v36, vcc
	v_cndmask_b32_e64 v33, v33, v37, s[0:1]
	v_cndmask_b32_e32 v34, v38, v34, vcc
	v_cndmask_b32_e64 v4, v4, v35, s[4:5]
	v_cndmask_b32_e64 v35, v35, v33, s[4:5]
	v_sub_u32_e32 v39, 32, v62
	v_cndmask_b32_e64 v37, v37, v34, s[0:1]
	v_alignbit_b32 v40, v4, v35, v39
	v_cmp_eq_u32_e64 s[8:9], 0, v62
	v_cndmask_b32_e64 v33, v33, v37, s[4:5]
	v_cndmask_b32_e32 v32, v36, v32, vcc
	v_cndmask_b32_e64 v4, v40, v4, s[8:9]
	v_alignbit_b32 v38, v35, v33, v39
	v_cndmask_b32_e64 v32, v34, v32, s[0:1]
	v_cndmask_b32_e64 v35, v38, v35, s[8:9]
	v_bfe_u32 v41, v4, 29, 1
	v_cndmask_b32_e64 v32, v37, v32, s[4:5]
	v_alignbit_b32 v38, v4, v35, 30
	v_sub_u32_e32 v42, 0, v41
	v_alignbit_b32 v34, v33, v32, v39
	v_xor_b32_e32 v38, v38, v42
	v_cndmask_b32_e64 v33, v34, v33, s[8:9]
	v_alignbit_b32 v34, v35, v33, 30
	v_ffbh_u32_e32 v35, v38
	v_min_u32_e32 v35, 32, v35
	v_alignbit_b32 v32, v33, v32, 30
	v_xor_b32_e32 v34, v34, v42
	v_sub_u32_e32 v36, 31, v35
	v_xor_b32_e32 v32, v32, v42
	v_alignbit_b32 v37, v38, v34, v36
	v_alignbit_b32 v32, v34, v32, v36
	v_alignbit_b32 v33, v37, v32, 9
	v_ffbh_u32_e32 v34, v33
	v_min_u32_e32 v34, 32, v34
	v_lshrrev_b32_e32 v40, 29, v4
	v_not_b32_e32 v36, v34
	v_alignbit_b32 v32, v33, v32, v36
	v_lshlrev_b32_e32 v33, 31, v40
	v_or_b32_e32 v36, 0x33000000, v33
	v_add_lshl_u32 v34, v34, v35, 23
	v_lshrrev_b32_e32 v32, 9, v32
	v_sub_u32_e32 v34, v36, v34
	v_or_b32_e32 v33, 0.5, v33
	v_lshlrev_b32_e32 v35, 23, v35
	v_or_b32_e32 v32, v34, v32
	v_lshrrev_b32_e32 v34, 9, v37
	v_sub_u32_e32 v33, v33, v35
	v_or_b32_e32 v33, v34, v33
	v_mul_f32_e32 v34, 0x3fc90fda, v33
	v_fma_f32 v35, v33, s44, -v34
	v_fmac_f32_e32 v35, 0x33a22168, v33
	v_fmac_f32_e32 v35, 0x3fc90fda, v32
	v_lshrrev_b32_e32 v4, 30, v4
	v_add_f32_e32 v32, v34, v35
	v_add_u32_e32 v4, v41, v4

; DEV void phase_filter_mlp(const Params& p, char* smem) {
;     ...
;       {
;         float s = b3[u];
;         for (int k = 0; k < 64; ++k) s += h2[pp * 64 + k] * w3[k * 64 + u];
;         h3[pp * 64 + u] = sinf(fr[128 + u] * s);
.LBB0_72:
	v_lshl_add_u64 v[32:33], v[24:25], 0, s[0:1]
	global_load_dword v31, v[32:33], off
	global_load_dword v44, v[32:33], off offset:256
	global_load_dword v45, v[32:33], off offset:512
	global_load_dword v66, v[32:33], off offset:768
	global_load_dword v67, v[32:33], off offset:1024
	global_load_dword v68, v[32:33], off offset:1280
	global_load_dword v69, v[32:33], off offset:1536
	global_load_dword v70, v[32:33], off offset:1792
	global_load_dword v71, v[32:33], off offset:2048
	global_load_dword v72, v[32:33], off offset:2304
	global_load_dword v73, v[32:33], off offset:2560
	global_load_dword v74, v[32:33], off offset:2816
	global_load_dword v75, v[32:33], off offset:3072
	global_load_dword v76, v[32:33], off offset:3328
	global_load_dword v77, v[32:33], off offset:3584
	global_load_dword v78, v[32:33], off offset:3840
	s_add_u32 s0, s0, 0x1000
	s_addc_u32 s1, s1, 0
	v_lshl_add_u64 v[32:33], v[24:25], 0, s[0:1]
	global_load_dword v100, v[32:33], off
	global_load_dword v101, v[32:33], off offset:256
	global_load_dword v102, v[32:33], off offset:512
	global_load_dword v103, v[32:33], off offset:768
	global_load_dword v104, v[32:33], off offset:1024
	global_load_dword v105, v[32:33], off offset:1280
	global_load_dword v106, v[32:33], off offset:1536
	global_load_dword v107, v[32:33], off offset:1792
	global_load_dword v108, v[32:33], off offset:2048
	global_load_dword v109, v[32:33], off offset:2304
	global_load_dword v110, v[32:33], off offset:2560
	global_load_dword v111, v[32:33], off offset:2816
	global_load_dword v112, v[32:33], off offset:3072
	global_load_dword v113, v[32:33], off offset:3328
	global_load_dword v114, v[32:33], off offset:3584
	global_load_dword v115, v[32:33], off offset:3840
	s_add_u32 s0, s0, 0x1000
	s_addc_u32 s1, s1, 0
	v_lshl_add_u64 v[32:33], v[24:25], 0, s[0:1]
	global_load_dword v116, v[32:33], off
	global_load_dword v117, v[32:33], off offset:256
	global_load_dword v118, v[32:33], off offset:512
	global_load_dword v119, v[32:33], off offset:768
	global_load_dword v120, v[32:33], off offset:1024
	global_load_dword v121, v[32:33], off offset:1280
	global_load_dword v122, v[32:33], off offset:1536
	global_load_dword v123, v[32:33], off offset:1792
	global_load_dword v124, v[32:33], off offset:2048
	global_load_dword v125, v[32:33], off offset:2304
	global_load_dword v126, v[32:33], off offset:2560
	global_load_dword v127, v[32:33], off offset:2816
	global_load_dword v128, v[32:33], off offset:3072
	global_load_dword v129, v[32:33], off offset:3328
	global_load_dword v130, v[32:33], off offset:3584
	global_load_dword v131, v[32:33], off offset:3840
	s_add_u32 s0, s0, 0x1000
	s_addc_u32 s1, s1, 0
	v_lshl_add_u64 v[32:33], v[24:25], 0, s[0:1]
	global_load_dword v132, v[32:33], off
	global_load_dword v133, v[32:33], off offset:256
	global_load_dword v134, v[32:33], off offset:512
	global_load_dword v135, v[32:33], off offset:768
	global_load_dword v136, v[32:33], off offset:1024
	global_load_dword v137, v[32:33], off offset:1280
	global_load_dword v138, v[32:33], off offset:1536
	global_load_dword v139, v[32:33], off offset:1792
	global_load_dword v140, v[32:33], off offset:2048
	global_load_dword v141, v[32:33], off offset:2304
	global_load_dword v142, v[32:33], off offset:2560
	global_load_dword v143, v[32:33], off offset:2816
	global_load_dword v144, v[32:33], off offset:3072
	global_load_dword v145, v[32:33], off offset:3328
	global_load_dword v146, v[32:33], off offset:3584
	global_load_dword v147, v[32:33], off offset:3840
	s_add_u32 s0, s0, 0x1000
	s_addc_u32 s1, s1, 0
	ds_read_b128 v[32:35], v30
	ds_read_b128 v[36:39], v30 offset:16
	ds_read_b128 v[40:43], v30 offset:32
	ds_read_b128 v[62:65], v30 offset:48
	v_add_u32_e32 v30, 64, v30
	s_waitcnt vmcnt(63) lgkmcnt(3)
	v_fmac_f32_e32 v4, v32, v31
	s_waitcnt vmcnt(62)
	v_fmac_f32_e32 v4, v33, v44
	s_waitcnt vmcnt(61)
	v_fmac_f32_e32 v4, v34, v45
	s_waitcnt vmcnt(60)
	v_fmac_f32_e32 v4, v35, v66
	s_waitcnt vmcnt(59) lgkmcnt(2)
	v_fmac_f32_e32 v4, v36, v67
	s_waitcnt vmcnt(58)
	v_fmac_f32_e32 v4, v37, v68
	s_waitcnt vmcnt(57)
	v_fmac_f32_e32 v4, v38, v69
	s_waitcnt vmcnt(56)
	v_fmac_f32_e32 v4, v39, v70
	s_waitcnt vmcnt(55) lgkmcnt(1)
	v_fmac_f32_e32 v4, v40, v71
	s_waitcnt vmcnt(54)
	v_fmac_f32_e32 v4, v41, v72
	s_waitcnt vmcnt(53)
	v_fmac_f32_e32 v4, v42, v73
	s_waitcnt vmcnt(52)
	v_fmac_f32_e32 v4, v43, v74
	s_waitcnt vmcnt(51) lgkmcnt(0)
	v_fmac_f32_e32 v4, v62, v75
	s_waitcnt vmcnt(50)
	v_fmac_f32_e32 v4, v63, v76
	s_waitcnt vmcnt(49)
	v_fmac_f32_e32 v4, v64, v77
	s_waitcnt vmcnt(48)
	v_fmac_f32_e32 v4, v65, v78
	ds_read_b128 v[32:35], v30
	ds_read_b128 v[36:39], v30 offset:16
	ds_read_b128 v[40:43], v30 offset:32
	ds_read_b128 v[62:65], v30 offset:48
	v_add_u32_e32 v30, 64, v30
	s_waitcnt vmcnt(47) lgkmcnt(3)
	v_fmac_f32_e32 v4, v32, v100
	s_waitcnt vmcnt(46)
	v_fmac_f32_e32 v4, v33, v101
	s_waitcnt vmcnt(45)
	v_fmac_f32_e32 v4, v34, v102
	s_waitcnt vmcnt(44)
	v_fmac_f32_e32 v4, v35, v103
	s_waitcnt vmcnt(43) lgkmcnt(2)
	v_fmac_f32_e32 v4, v36, v104
	s_waitcnt vmcnt(42)
	v_fmac_f32_e32 v4, v37, v105
	s_waitcnt vmcnt(41)
	v_fmac_f32_e32 v4, v38, v106
	s_waitcnt vmcnt(40)
	v_fmac_f32_e32 v4, v39, v107
	s_waitcnt vmcnt(39) lgkmcnt(1)
	v_fmac_f32_e32 v4, v40, v108
	s_waitcnt vmcnt(38)
	v_fmac_f32_e32 v4, v41, v109
	s_waitcnt vmcnt(37)
	v_fmac_f32_e32 v4, v42, v110
	s_waitcnt vmcnt(36)
	v_fmac_f32_e32 v4, v43, v111
	s_waitcnt vmcnt(35) lgkmcnt(0)
; DEV void phase_filter_mlp(const Params& p, char* smem) {
;     ...
;         for (int k = 0; k < 64; ++k) s += h2[pp * 64 + k] * w3[k * 64 + u];
;         h3[pp * 64 + u] = sinf(fr[128 + u] * s);
	v_fmac_f32_e32 v4, v62, v112
	s_waitcnt vmcnt(34)
	v_fmac_f32_e32 v4, v63, v113
	s_waitcnt vmcnt(33)
	v_fmac_f32_e32 v4, v64, v114
	s_waitcnt vmcnt(32)
	v_fmac_f32_e32 v4, v65, v115
	ds_read_b128 v[32:35], v30
	ds_read_b128 v[36:39], v30 offset:16
	ds_read_b128 v[40:43], v30 offset:32
	ds_read_b128 v[62:65], v30 offset:48
	v_add_u32_e32 v30, 64, v30
	s_waitcnt vmcnt(31) lgkmcnt(3)
	v_fmac_f32_e32 v4, v32, v116
	s_waitcnt vmcnt(30)
	v_fmac_f32_e32 v4, v33, v117
	s_waitcnt vmcnt(29)
	v_fmac_f32_e32 v4, v34, v118
	s_waitcnt vmcnt(28)
	v_fmac_f32_e32 v4, v35, v119
	s_waitcnt vmcnt(27) lgkmcnt(2)
	v_fmac_f32_e32 v4, v36, v120
	s_waitcnt vmcnt(26)
	v_fmac_f32_e32 v4, v37, v121
	s_waitcnt vmcnt(25)
	v_fmac_f32_e32 v4, v38, v122
	s_waitcnt vmcnt(24)
	v_fmac_f32_e32 v4, v39, v123
	s_waitcnt vmcnt(23) lgkmcnt(1)
	v_fmac_f32_e32 v4, v40, v124
	s_waitcnt vmcnt(22)
	v_fmac_f32_e32 v4, v41, v125
	s_waitcnt vmcnt(21)
	v_fmac_f32_e32 v4, v42, v126
	s_waitcnt vmcnt(20)
	v_fmac_f32_e32 v4, v43, v127
	s_waitcnt vmcnt(19) lgkmcnt(0)
	v_fmac_f32_e32 v4, v62, v128
	s_waitcnt vmcnt(18)
	v_fmac_f32_e32 v4, v63, v129
	s_waitcnt vmcnt(17)
	v_fmac_f32_e32 v4, v64, v130
	s_waitcnt vmcnt(16)
	v_fmac_f32_e32 v4, v65, v131
	ds_read_b128 v[32:35], v30
	ds_read_b128 v[36:39], v30 offset:16
	ds_read_b128 v[40:43], v30 offset:32
	ds_read_b128 v[62:65], v30 offset:48
	v_add_u32_e32 v30, 64, v30
	s_waitcnt vmcnt(15) lgkmcnt(3)
	v_fmac_f32_e32 v4, v32, v132
	s_waitcnt vmcnt(14)
	v_fmac_f32_e32 v4, v33, v133
	s_waitcnt vmcnt(13)
	v_fmac_f32_e32 v4, v34, v134
	s_waitcnt vmcnt(12)
	v_fmac_f32_e32 v4, v35, v135
	s_waitcnt vmcnt(11) lgkmcnt(2)
	v_fmac_f32_e32 v4, v36, v136
	s_waitcnt vmcnt(10)
	v_fmac_f32_e32 v4, v37, v137
	s_waitcnt vmcnt(9)
	v_fmac_f32_e32 v4, v38, v138
	s_waitcnt vmcnt(8)
	v_fmac_f32_e32 v4, v39, v139
	s_waitcnt vmcnt(7) lgkmcnt(1)
	v_fmac_f32_e32 v4, v40, v140
	s_waitcnt vmcnt(6)
	v_fmac_f32_e32 v4, v41, v141
	s_waitcnt vmcnt(5)
	v_fmac_f32_e32 v4, v42, v142
	s_waitcnt vmcnt(4)
	v_fmac_f32_e32 v4, v43, v143
	s_waitcnt vmcnt(3) lgkmcnt(0)
	v_fmac_f32_e32 v4, v62, v144
	s_waitcnt vmcnt(2)
	v_fmac_f32_e32 v4, v63, v145
	s_waitcnt vmcnt(1)
	v_fmac_f32_e32 v4, v64, v146
	s_waitcnt vmcnt(0)
	v_fmac_f32_e32 v4, v65, v147
	global_load_dword v30, v[8:9], off offset:512
	s_waitcnt vmcnt(0)
	v_mul_f32_e32 v30, v4, v30
	v_and_b32_e32 v31, 0x7fffffff, v30
	v_cmp_nlt_f32_e64 s[0:1], |v30|, s36
	s_and_saveexec_b64 s[4:5], s[0:1]
	s_xor_b64 s[20:21], exec, s[4:5]
	s_cbranch_execz .LBB0_75
	v_lshrrev_b32_e32 v4, 23, v31
	v_add_u32_e32 v4, 0xffffff88, v4
	v_cmp_lt_u32_e32 vcc, 63, v4
	s_nop 1
	v_cndmask_b32_e32 v32, 0, v55, vcc
	v_add_u32_e32 v4, v32, v4
	v_cmp_lt_u32_e64 s[0:1], 31, v4
	s_nop 1
	v_cndmask_b32_e64 v32, 0, v56, s[0:1]
	v_add_u32_e32 v4, v32, v4
	v_cmp_lt_u32_e64 s[4:5], 31, v4
	s_nop 1
	v_cndmask_b32_e64 v32, 0, v56, s[4:5]
	v_add_u32_e32 v62, v32, v4
	v_and_b32_e32 v4, 0x7fffff, v31
	v_or_b32_e32 v44, 0x800000, v4
	v_mad_u64_u32 v[32:33], s[8:9], v44, s37, 0
	v_mov_b32_e32 v4, v33
	v_mad_u64_u32 v[34:35], s[8:9], v44, s38, v[4:5]
	v_mov_b32_e32 v4, v35
	v_mad_u64_u32 v[36:37], s[8:9], v44, s39, v[4:5]
	v_mov_b32_e32 v4, v37
	v_mad_u64_u32 v[38:39], s[8:9], v44, s40, v[4:5]
	v_mov_b32_e32 v4, v39
	v_mad_u64_u32 v[40:41], s[8:9], v44, s41, v[4:5]
	v_mov_b32_e32 v4, v41
	v_mad_u64_u32 v[42:43], s[8:9], v44, s42, v[4:5]
	v_mov_b32_e32 v4, v43
	v_mad_u64_u32 v[44:45], s[8:9], v44, s43, v[4:5]
	v_cndmask_b32_e32 v33, v42, v38, vcc
	v_cndmask_b32_e32 v4, v44, v40, vcc
	v_cndmask_b32_e32 v37, v45, v42, vcc
	v_cndmask_b32_e64 v35, v4, v33, s[0:1]
	v_cndmask_b32_e64 v4, v37, v4, s[0:1]
	v_cndmask_b32_e32 v37, v40, v36, vcc
	v_cndmask_b32_e64 v33, v33, v37, s[0:1]
	v_cndmask_b32_e32 v34, v38, v34, vcc
	v_cndmask_b32_e64 v4, v4, v35, s[4:5]
	v_cndmask_b32_e64 v35, v35, v33, s[4:5]
	v_sub_u32_e32 v39, 32, v62
	v_cndmask_b32_e64 v37, v37, v34, s[0:1]
	v_alignbit_b32 v40, v4, v35, v39
	v_cmp_eq_u32_e64 s[8:9], 0, v62
	v_cndmask_b32_e64 v33, v33, v37, s[4:5]
	v_cndmask_b32_e32 v32, v36, v32, vcc
	v_cndmask_b32_e64 v4, v40, v4, s[8:9]
	v_alignbit_b32 v38, v35, v33, v39
	v_cndmask_b32_e64 v32, v34, v32, s[0:1]
	v_cndmask_b32_e64 v35, v38, v35, s[8:9]
	v_bfe_u32 v41, v4, 29, 1
	v_cndmask_b32_e64 v32, v37, v32, s[4:5]
	v_alignbit_b32 v38, v4, v35, 30
	v_sub_u32_e32 v42, 0, v41
	v_alignbit_b32 v34, v33, v32, v39
	v_xor_b32_e32 v38, v38, v42
	v_cndmask_b32_e64 v33, v34, v33, s[8:9]
	v_alignbit_b32 v34, v35, v33, 30
	v_ffbh_u32_e32 v35, v38
	v_min_u32_e32 v35, 32, v35
	v_alignbit_b32 v32, v33, v32, 30
	v_xor_b32_e32 v34, v34, v42
	v_sub_u32_e32 v36, 31, v35
	v_xor_b32_e32 v32, v32, v42
	v_alignbit_b32 v37, v38, v34, v36
	v_alignbit_b32 v32, v34, v32, v36
	v_alignbit_b32 v33, v37, v32, 9
	v_ffbh_u32_e32 v34, v33
	v_min_u32_e32 v34, 32, v34
	v_lshrrev_b32_e32 v40, 29, v4
	v_not_b32_e32 v36, v34
	v_alignbit_b32 v32, v33, v32, v36
	v_lshlrev_b32_e32 v33, 31, v40
	v_or_b32_e32 v36, 0x33000000, v33
	v_add_lshl_u32 v34, v34, v35, 23
	v_lshrrev_b32_e32 v32, 9, v32
	v_sub_u32_e32 v34, v36, v34
	v_or_b32_e32 v33, 0.5, v33
	v_lshlrev_b32_e32 v35, 23, v35
	v_or_b32_e32 v32, v34, v32
	v_lshrrev_b32_e32 v34, 9, v37
	v_sub_u32_e32 v33, v33, v35
	v_or_b32_e32 v33, v34, v33
	v_mul_f32_e32 v34, 0x3fc90fda, v33
	v_fma_f32 v35, v33, s44, -v34
	v_fmac_f32_e32 v35, 0x33a22168, v33
	v_fmac_f32_e32 v35, 0x3fc90fda, v32
	v_lshrrev_b32_e32 v4, 30, v4
	v_add_f32_e32 v32, v34, v35
	v_add_u32_e32 v4, v41, v4
